# norm phases P6/P9/P13: gain vector kept resident (was re-loaded per row), one counted wait per row pair placed before the next pair's loads are issued
# speedup vs baseline: 1.0030x; 1.0030x over previous
.LBB0_698:
	s_and_b64 s[4:5], s[4:5], s[6:7]
	s_andn2_b64 vcc, exec, s[4:5]
	s_cbranch_vccnz .LBB0_716
	s_waitcnt vmcnt(0)
	v_mov_b32_e32 v1, s1
	v_mov_b32_e32 v0, v254
	v_mov_b32_e32 v4, s0
	v_mov_b32_e32 v5, s1
	v_readfirstlane_b32 s6, v4
	v_mov_b32_e32 v4, s0
	v_readfirstlane_b32 s4, v0
	v_readfirstlane_b32 s10, v4
	v_readfirstlane_b32 s11, v5
	v_mov_b32_e32 v4, s0
	v_mov_b32_e32 v5, s1
	s_lshl_b32 s3, s2, 3
	s_ashr_i32 s4, s4, 6
	v_mov_b32_e32 v2, s0
	s_add_i32 s16, s4, s3
	v_mov_b32_e32 v3, s0
	v_readfirstlane_b32 s7, v1
	v_mov_b32_e32 v1, s1
	v_readfirstlane_b32 s4, v4
	v_mov_b32_e32 v4, s1
	v_readfirstlane_b32 s5, v5
	s_cmpk_gt_i32 s16, 0x7fff
	v_readfirstlane_b32 s8, v3
	v_readfirstlane_b32 s9, v4
	v_readfirstlane_b32 s12, v2
	v_readfirstlane_b32 s13, v1
	s_cbranch_scc1 .LBB0_716
	s_load_dwordx2 s[12:13], s[12:13], 0xc0
	s_nop 0
	s_load_dwordx2 s[14:15], s[6:7], 0xc0
	s_load_dwordx2 s[18:19], s[10:11], 0xc0
	s_waitcnt lgkmcnt(0)
	s_lshl_b32 s17, s33, 3
	s_lshl_b32 s3, s33, 4
	v_and_b32_e32 v2, 63, v0
	s_add_u32 s22, s12, 0x3720c00
	s_addc_u32 s23, s13, 0
	s_add_i32 s6, s16, s17
	v_lshlrev_b32_e32 v18, 3, v2
	v_mov_b32_e32 v19, 0
	s_cmp_lt_i32 s6, 0x8000
	v_lshl_add_u64 v[0:1], s[14:15], 0, v[18:19]
	s_mov_b64 s[10:11], 0x4000000
	s_cselect_b32 s6, s6, s16
	v_lshl_add_u64 v[20:21], v[0:1], 0, s[10:11]
	v_lshl_add_u64 v[0:1], s[18:19], 0, v[18:19]
	s_mov_b64 s[12:13], 0x8000000
	s_ashr_i32 s17, s16, 31
	v_lshl_add_u64 v[22:23], v[0:1], 0, s[12:13]
	s_lshl_b64 s[12:13], s[16:17], 11
	v_lshl_add_u64 v[0:1], v[20:21], 0, s[12:13]
	s_ashr_i32 s7, s6, 31
	global_load_dwordx2 v[24:25], v[0:1], off
	global_load_dwordx2 v[26:27], v[0:1], off offset:512
	global_load_dwordx2 v[28:29], v[0:1], off offset:1024
	global_load_dwordx2 v[30:31], v[0:1], off offset:1536
	v_lshl_add_u64 v[0:1], v[22:23], 0, s[12:13]
	s_lshl_b64 s[12:13], s[6:7], 11
	global_load_dwordx2 v[32:33], v[0:1], off
	global_load_dwordx2 v[34:35], v[0:1], off offset:512
	global_load_dwordx2 v[36:37], v[0:1], off offset:1024
	global_load_dwordx2 v[38:39], v[0:1], off offset:1536
	v_lshl_add_u64 v[0:1], v[20:21], 0, s[12:13]
	global_load_dwordx2 v[44:45], v[0:1], off
	global_load_dwordx2 v[46:47], v[0:1], off offset:512
	global_load_dwordx2 v[48:49], v[0:1], off offset:1024
	global_load_dwordx2 v[50:51], v[0:1], off offset:1536
	v_lshl_add_u64 v[0:1], v[22:23], 0, s[12:13]
	global_load_dwordx2 v[52:53], v[0:1], off
	global_load_dwordx2 v[54:55], v[0:1], off offset:512
	global_load_dwordx2 v[56:57], v[0:1], off offset:1024
	global_load_dwordx2 v[58:59], v[0:1], off offset:1536
	s_load_dwordx2 s[12:13], s[4:5], 0x18
	s_load_dwordx2 s[14:15], s[8:9], 0xc0
	v_lshlrev_b32_e32 v0, 4, v2
	v_mov_b32_e32 v1, v19
	v_cmp_eq_u32_e64 s[4:5], 0, v2
	s_waitcnt lgkmcnt(0)
	v_lshl_add_u64 v[40:41], s[12:13], 0, v[0:1]
	v_lshl_add_u64 v[0:1], s[14:15], 0, v[18:19]
	v_lshl_add_u64 v[42:43], v[0:1], 0, s[10:11]
	v_mbcnt_lo_u32_b32 v0, -1, 0
	v_mbcnt_hi_u32_b32 v0, -1, v0
	v_and_b32_e32 v1, 64, v0
	v_add_u32_e32 v1, 64, v1
	v_xor_b32_e32 v2, 1, v0
	v_cmp_lt_i32_e32 vcc, v2, v1
	s_lshl_b32 s24, s33, 5
	s_mul_i32 s25, s33, 40
	v_cndmask_b32_e32 v2, v0, v2, vcc
	v_lshlrev_b32_e32 v18, 2, v2
	v_xor_b32_e32 v2, 2, v0
	v_cmp_lt_i32_e32 vcc, v2, v1
	s_mul_i32 s26, s33, 24
	v_mov_b32_e32 v79, 0x358637bd
	v_cndmask_b32_e32 v2, v0, v2, vcc
	v_lshlrev_b32_e32 v74, 2, v2
	v_xor_b32_e32 v2, 4, v0
	v_cmp_lt_i32_e32 vcc, v2, v1
	s_mov_b32 s12, s16
	s_nop 0
	v_cndmask_b32_e32 v2, v0, v2, vcc
	v_lshlrev_b32_e32 v75, 2, v2
	v_xor_b32_e32 v2, 8, v0
	v_cmp_lt_i32_e32 vcc, v2, v1
	s_nop 1
	v_cndmask_b32_e32 v2, v0, v2, vcc
	v_lshlrev_b32_e32 v76, 2, v2
	v_xor_b32_e32 v2, 16, v0
	v_cmp_lt_i32_e32 vcc, v2, v1
	s_nop 1
	v_cndmask_b32_e32 v2, v0, v2, vcc
	v_lshlrev_b32_e32 v77, 2, v2
	v_xor_b32_e32 v2, 32, v0
	v_cmp_lt_i32_e32 vcc, v2, v1
	s_nop 1
	v_cndmask_b32_e32 v0, v0, v2, vcc
	v_lshlrev_b32_e32 v78, 2, v0
	global_load_dwordx4 v[200:203], v[40:41], off
	global_load_dwordx4 v[204:207], v[40:41], off offset:1024
	global_load_dwordx4 v[208:211], v[40:41], off offset:2048
	global_load_dwordx4 v[212:215], v[40:41], off offset:3072
	s_waitcnt vmcnt(0)
	s_branch .LBB0_703

.LBB0_703:
	s_waitcnt vmcnt(10)
	s_add_i32 s14, s16, s3
	s_cmp_lt_i32 s14, 0x8000
	s_cselect_b64 s[18:19], -1, 0
	s_cmpk_gt_i32 s14, 0x7fff
	s_cbranch_scc1 .LBB0_705
	s_add_i32 s7, s26, s16
	s_cmp_lt_i32 s7, 0x8000
	s_cselect_b32 s8, s7, s14
	s_ashr_i32 s15, s14, 31
	s_lshl_b64 s[10:11], s[14:15], 11
	v_lshl_add_u64 v[8:9], v[20:21], 0, s[10:11]
	s_ashr_i32 s9, s8, 31
	global_load_dwordx2 v[0:1], v[8:9], off
	global_load_dwordx2 v[2:3], v[8:9], off offset:512
	global_load_dwordx2 v[4:5], v[8:9], off offset:1024
	global_load_dwordx2 v[6:7], v[8:9], off offset:1536
	v_lshl_add_u64 v[8:9], v[22:23], 0, s[10:11]
	s_lshl_b64 s[10:11], s[8:9], 11
	v_lshl_add_u64 v[66:67], v[20:21], 0, s[10:11]
	s_waitcnt lgkmcnt(0)
	v_lshl_add_u64 v[80:81], v[22:23], 0, s[10:11]
	global_load_dwordx2 v[16:17], v[8:9], off
	global_load_dwordx2 v[60:61], v[8:9], off offset:512
	global_load_dwordx2 v[62:63], v[8:9], off offset:1024
	global_load_dwordx2 v[64:65], v[8:9], off offset:1536
	s_nop 0
	global_load_dwordx2 v[8:9], v[66:67], off
	global_load_dwordx2 v[10:11], v[66:67], off offset:512
	global_load_dwordx2 v[12:13], v[66:67], off offset:1024
	global_load_dwordx2 v[14:15], v[66:67], off offset:1536
	s_nop 0
	global_load_dwordx2 v[66:67], v[80:81], off
	global_load_dwordx2 v[68:69], v[80:81], off offset:512
	global_load_dwordx2 v[70:71], v[80:81], off offset:1024
	global_load_dwordx2 v[72:73], v[80:81], off offset:1536
	s_mov_b32 s10, s14
.LBB0_705:
	v_and_b32_e32 v99, 0xffff0000, v33
	v_and_b32_e32 v98, 0xffff0000, v32
	v_lshlrev_b32_e32 v97, 16, v33
	v_lshlrev_b32_e32 v96, 16, v32
	v_pk_mul_f32 v[84:85], v[98:99], v[98:99]
	s_waitcnt lgkmcnt(0)
	v_pk_fma_f32 v[84:85], v[96:97], v[96:97], v[84:85]
	v_and_b32_e32 v105, 0xffff0000, v35
	v_and_b32_e32 v104, 0xffff0000, v34
	v_pk_add_f32 v[100:101], v[84:85], v[84:85] op_sel_hi:[0,1]
	v_lshlrev_b32_e32 v103, 16, v35
	v_lshlrev_b32_e32 v102, 16, v34
	v_pk_mul_f32 v[92:93], v[104:105], v[104:105]
	v_pk_fma_f32 v[92:93], v[102:103], v[102:103], v[92:93]
	v_lshlrev_b32_e32 v108, 16, v36
	v_pk_add_f32 v[106:107], v[92:93], v[92:93] op_sel_hi:[0,1]
	v_and_b32_e32 v109, 0xffff0000, v36
	v_lshlrev_b32_e32 v114, 16, v37
	v_lshlrev_b32_e32 v110, 16, v38
	v_mul_f32_e32 v111, v108, v108
	v_mul_f32_e32 v113, v109, v109
	v_and_b32_e32 v115, 0xffff0000, v37
	v_mul_f32_e32 v100, v114, v114
	v_mov_b32_e32 v112, v110
	v_pk_fma_f32 v[116:117], v[114:115], v[114:115], v[100:101] op_sel_hi:[1,1,0]
	v_and_b32_e32 v132, 0xffff0000, v38
	v_lshlrev_b32_e32 v118, 16, v39
	v_and_b32_e32 v119, 0xffff0000, v39
	v_pk_add_f32 v[112:113], v[110:111], v[112:113]
	v_mul_f32_e32 v116, v132, v132
	v_mul_f32_e32 v100, v118, v118
	v_mul_f32_e32 v106, v119, v119
	v_mul_f32_e32 v120, v110, v110
	v_mov_b32_e32 v121, v113
	v_pk_add_f32 v[112:113], v[120:121], v[116:117]
	v_pk_add_f32 v[100:101], v[100:101], v[106:107]
	v_mov_b32_e32 v128, v96
	v_pk_add_f32 v[100:101], v[112:113], v[100:101]
	v_mov_b32_e32 v129, v98
	v_add_f32_e32 v100, v100, v101
	ds_bpermute_b32 v101, v18, v100
	v_mov_b32_e32 v98, v97
	v_mov_b32_e32 v131, v104
	v_mov_b32_e32 v104, v103
	v_and_b32_e32 v117, 0xffff0000, v27
	s_waitcnt lgkmcnt(0)
	v_add_f32_e32 v106, v100, v101
	ds_bpermute_b32 v107, v74, v106
	v_lshlrev_b32_e32 v100, 16, v24
	v_and_b32_e32 v101, 0xffff0000, v24
	v_lshlrev_b32_e32 v120, 16, v28
	v_and_b32_e32 v121, 0xffff0000, v28
	s_waitcnt lgkmcnt(0)
	v_add_f32_e32 v111, v106, v107
	ds_bpermute_b32 v116, v75, v111
	v_lshlrev_b32_e32 v106, 16, v25
	v_and_b32_e32 v107, 0xffff0000, v25
	v_and_b32_e32 v127, 0xffff0000, v31
	v_lshlrev_b32_e32 v112, 16, v26
	s_waitcnt lgkmcnt(0)
	v_add_f32_e32 v111, v111, v116
	ds_bpermute_b32 v122, v76, v111
	v_lshlrev_b32_e32 v116, 16, v27
	v_and_b32_e32 v113, 0xffff0000, v26
	v_lshlrev_b32_e32 v124, 16, v30
	v_and_b32_e32 v125, 0xffff0000, v30
	s_waitcnt lgkmcnt(0)
	v_add_f32_e32 v111, v111, v122
	ds_bpermute_b32 v126, v77, v111
	v_lshlrev_b32_e32 v122, 16, v29
	v_and_b32_e32 v123, 0xffff0000, v29
	s_ashr_i32 s13, s12, 31
	s_lshl_b64 s[20:21], s[12:13], 11
	s_waitcnt lgkmcnt(0)
	v_add_f32_e32 v111, v111, v126
	ds_bpermute_b32 v130, v78, v111
	v_lshlrev_b32_e32 v126, 16, v31
	s_waitcnt lgkmcnt(0)
	v_add_f32_e32 v96, v111, v130
	v_fmamk_f32 v96, v96, 0x3a800000, v79
	v_rsq_f32_e32 v96, v96
	v_mov_b32_e32 v130, v102
	v_mov_b32_e32 v111, v132
	v_pk_mul_f32 v[98:99], v[96:97], v[98:99] op_sel_hi:[0,1]
	v_pk_fma_f32 v[82:83], v[202:203], v[98:99], v[106:107]
	v_pk_mul_f32 v[98:99], v[96:97], v[104:105] op_sel_hi:[0,1]
	v_pk_mul_f32 v[128:129], v[96:97], v[128:129] op_sel_hi:[0,1]
	v_pk_mul_f32 v[130:131], v[96:97], v[130:131] op_sel_hi:[0,1]
	v_pk_fma_f32 v[80:81], v[200:201], v[128:129], v[100:101]
	v_pk_mul_f32 v[100:101], v[114:115], v[96:97] op_sel_hi:[1,0]
	v_pk_fma_f32 v[86:87], v[206:207], v[98:99], v[116:117]
	v_pk_mul_f32 v[98:99], v[108:109], v[96:97] op_sel_hi:[1,0]
	v_pk_fma_f32 v[84:85], v[204:205], v[130:131], v[112:113]
	v_pk_fma_f32 v[88:89], v[208:209], v[98:99], v[120:121]
	v_pk_mul_f32 v[98:99], v[110:111], v[96:97] op_sel_hi:[1,0]
	v_pk_mul_f32 v[96:97], v[118:119], v[96:97] op_sel_hi:[1,0]
	v_pk_fma_f32 v[90:91], v[210:211], v[100:101], v[122:123]
	v_pk_fma_f32 v[94:95], v[214:215], v[96:97], v[126:127]
	v_mul_f32_e32 v96, v81, v81
	v_mul_f32_e32 v97, v83, v83
	v_fmac_f32_e32 v96, v80, v80
	v_fmac_f32_e32 v97, v82, v82
	v_pk_fma_f32 v[92:93], v[212:213], v[98:99], v[124:125]
	v_add_f32_e32 v96, v96, v97
	v_mul_f32_e32 v97, v85, v85
	v_mul_f32_e32 v98, v87, v87
	v_fmac_f32_e32 v97, v84, v84
	v_fmac_f32_e32 v98, v86, v86
	v_add_f32_e32 v97, v97, v98
	v_add_f32_e32 v96, v96, v97
	v_mul_f32_e32 v97, v89, v89
	v_mul_f32_e32 v98, v91, v91
	v_fmac_f32_e32 v97, v88, v88
	v_fmac_f32_e32 v98, v90, v90
	v_add_f32_e32 v97, v97, v98
	v_add_f32_e32 v96, v97, v96
	v_mul_f32_e32 v97, v93, v93
	v_mul_f32_e32 v98, v95, v95
	v_fmac_f32_e32 v97, v92, v92
	v_fmac_f32_e32 v98, v94, v94
	v_add_f32_e32 v97, v97, v98
	v_add_f32_e32 v96, v97, v96
	ds_bpermute_b32 v97, v18, v96
	v_cvt_pk_bf16_f32 v80, v80, v81
	v_cvt_pk_bf16_f32 v81, v82, v83
	s_waitcnt lgkmcnt(0)
	v_add_f32_e32 v96, v96, v97
	ds_bpermute_b32 v97, v74, v96
	s_waitcnt lgkmcnt(0)
	v_add_f32_e32 v98, v96, v97
	ds_bpermute_b32 v99, v75, v98
	v_lshl_add_u64 v[96:97], v[42:43], 0, s[20:21]
	global_store_dwordx2 v[96:97], v[80:81], off sc1
	v_cvt_pk_bf16_f32 v80, v84, v85
	v_cvt_pk_bf16_f32 v81, v86, v87
	s_waitcnt lgkmcnt(0)
	v_add_f32_e32 v98, v98, v99
	ds_bpermute_b32 v99, v76, v98
	global_store_dwordx2 v[96:97], v[80:81], off offset:512 sc1
	v_cvt_pk_bf16_f32 v82, v88, v89
	v_cvt_pk_bf16_f32 v83, v90, v91
	global_store_dwordx2 v[96:97], v[82:83], off offset:1024 sc1
	s_waitcnt lgkmcnt(0)
	v_add_f32_e32 v84, v98, v99
	ds_bpermute_b32 v85, v77, v84
	v_cvt_pk_bf16_f32 v82, v92, v93
	v_cvt_pk_bf16_f32 v83, v94, v95
	global_store_dwordx2 v[96:97], v[82:83], off offset:1536 sc1
	s_waitcnt lgkmcnt(0)
	v_add_f32_e32 v80, v84, v85
	ds_bpermute_b32 v81, v78, v80
	s_and_saveexec_b64 s[20:21], s[4:5]
	s_cbranch_execz .LBB0_707
	s_waitcnt lgkmcnt(0)
	v_add_f32_e32 v80, v80, v81
	v_fmamk_f32 v80, v80, 0x3a800000, v79
	v_rsq_f32_e32 v80, v80
	s_lshl_b64 s[28:29], s[12:13], 2
	s_add_u32 s28, s22, s28
	s_addc_u32 s29, s23, s29
	global_store_dword v19, v80, s[28:29] sc1
.LBB0_707:
	s_or_b64 exec, exec, s[20:21]
	v_and_b32_e32 v99, 0xffff0000, v53
	v_and_b32_e32 v98, 0xffff0000, v52
	v_lshlrev_b32_e32 v97, 16, v53
	v_lshlrev_b32_e32 v96, 16, v52
	v_pk_mul_f32 v[84:85], v[98:99], v[98:99]
	s_waitcnt lgkmcnt(0)
	v_pk_fma_f32 v[84:85], v[96:97], v[96:97], v[84:85]
	v_and_b32_e32 v105, 0xffff0000, v55
	v_and_b32_e32 v104, 0xffff0000, v54
	v_pk_add_f32 v[100:101], v[84:85], v[84:85] op_sel_hi:[0,1]
	v_lshlrev_b32_e32 v103, 16, v55
	v_lshlrev_b32_e32 v102, 16, v54
	v_pk_mul_f32 v[92:93], v[104:105], v[104:105]
	v_pk_fma_f32 v[92:93], v[102:103], v[102:103], v[92:93]
	v_lshlrev_b32_e32 v108, 16, v56
	v_pk_add_f32 v[106:107], v[92:93], v[92:93] op_sel_hi:[0,1]
	v_and_b32_e32 v109, 0xffff0000, v56
	v_lshlrev_b32_e32 v114, 16, v57
	v_lshlrev_b32_e32 v110, 16, v58
	v_mul_f32_e32 v111, v108, v108
	v_mul_f32_e32 v113, v109, v109
	v_and_b32_e32 v115, 0xffff0000, v57
	v_mul_f32_e32 v100, v114, v114
	v_mov_b32_e32 v112, v110
	v_pk_fma_f32 v[116:117], v[114:115], v[114:115], v[100:101] op_sel_hi:[1,1,0]
	v_and_b32_e32 v132, 0xffff0000, v58
	v_lshlrev_b32_e32 v118, 16, v59
	v_and_b32_e32 v119, 0xffff0000, v59
	v_pk_add_f32 v[112:113], v[110:111], v[112:113]
	v_mul_f32_e32 v116, v132, v132
	v_mul_f32_e32 v100, v118, v118
	v_mul_f32_e32 v106, v119, v119
	v_mul_f32_e32 v120, v110, v110
	v_mov_b32_e32 v121, v113
	v_pk_add_f32 v[112:113], v[120:121], v[116:117]
	v_pk_add_f32 v[100:101], v[100:101], v[106:107]
	v_mov_b32_e32 v128, v96
	v_pk_add_f32 v[100:101], v[112:113], v[100:101]
	v_mov_b32_e32 v129, v98
	v_add_f32_e32 v100, v100, v101
	ds_bpermute_b32 v101, v18, v100
	v_mov_b32_e32 v98, v97
	v_mov_b32_e32 v131, v104
	v_mov_b32_e32 v104, v103
	v_and_b32_e32 v117, 0xffff0000, v47
	s_waitcnt lgkmcnt(0)
	v_add_f32_e32 v106, v100, v101
	ds_bpermute_b32 v107, v74, v106
	v_lshlrev_b32_e32 v100, 16, v44
	v_and_b32_e32 v101, 0xffff0000, v44
	v_lshlrev_b32_e32 v120, 16, v48
	v_and_b32_e32 v121, 0xffff0000, v48
	s_waitcnt lgkmcnt(0)
	v_add_f32_e32 v111, v106, v107
	ds_bpermute_b32 v116, v75, v111
	v_lshlrev_b32_e32 v106, 16, v45
	v_and_b32_e32 v107, 0xffff0000, v45
	v_and_b32_e32 v127, 0xffff0000, v51
	v_lshlrev_b32_e32 v112, 16, v46
	s_waitcnt lgkmcnt(0)
	v_add_f32_e32 v111, v111, v116
	ds_bpermute_b32 v122, v76, v111
	v_lshlrev_b32_e32 v116, 16, v47
	v_and_b32_e32 v113, 0xffff0000, v46
	v_lshlrev_b32_e32 v124, 16, v50
	v_and_b32_e32 v125, 0xffff0000, v50
	s_waitcnt lgkmcnt(0)
	v_add_f32_e32 v111, v111, v122
	ds_bpermute_b32 v126, v77, v111
	v_lshlrev_b32_e32 v122, 16, v49
	v_and_b32_e32 v123, 0xffff0000, v49
	s_ashr_i32 s7, s6, 31
	s_lshl_b64 s[20:21], s[6:7], 11
	s_waitcnt lgkmcnt(0)
	v_add_f32_e32 v111, v111, v126
	ds_bpermute_b32 v130, v78, v111
	v_lshlrev_b32_e32 v126, 16, v51
	s_waitcnt lgkmcnt(0)
	v_add_f32_e32 v96, v111, v130
	v_fmamk_f32 v96, v96, 0x3a800000, v79
	v_rsq_f32_e32 v96, v96
	v_mov_b32_e32 v130, v102
	v_mov_b32_e32 v111, v132
	v_pk_mul_f32 v[98:99], v[96:97], v[98:99] op_sel_hi:[0,1]
	v_pk_fma_f32 v[82:83], v[202:203], v[98:99], v[106:107]
	v_pk_mul_f32 v[98:99], v[96:97], v[104:105] op_sel_hi:[0,1]
	v_pk_mul_f32 v[128:129], v[96:97], v[128:129] op_sel_hi:[0,1]
	v_pk_mul_f32 v[130:131], v[96:97], v[130:131] op_sel_hi:[0,1]
	v_pk_fma_f32 v[80:81], v[200:201], v[128:129], v[100:101]
	v_pk_mul_f32 v[100:101], v[114:115], v[96:97] op_sel_hi:[1,0]
	v_pk_fma_f32 v[86:87], v[206:207], v[98:99], v[116:117]
	v_pk_mul_f32 v[98:99], v[108:109], v[96:97] op_sel_hi:[1,0]
	v_pk_fma_f32 v[84:85], v[204:205], v[130:131], v[112:113]
	v_pk_fma_f32 v[88:89], v[208:209], v[98:99], v[120:121]
	v_pk_mul_f32 v[98:99], v[110:111], v[96:97] op_sel_hi:[1,0]
	v_pk_mul_f32 v[96:97], v[118:119], v[96:97] op_sel_hi:[1,0]
	v_pk_fma_f32 v[90:91], v[210:211], v[100:101], v[122:123]
	v_pk_fma_f32 v[94:95], v[214:215], v[96:97], v[126:127]
	v_mul_f32_e32 v96, v81, v81
	v_mul_f32_e32 v97, v83, v83
	v_fmac_f32_e32 v96, v80, v80
	v_fmac_f32_e32 v97, v82, v82
	v_pk_fma_f32 v[92:93], v[212:213], v[98:99], v[124:125]
	v_add_f32_e32 v96, v96, v97
	v_mul_f32_e32 v97, v85, v85
	v_mul_f32_e32 v98, v87, v87
	v_fmac_f32_e32 v97, v84, v84
	v_fmac_f32_e32 v98, v86, v86
	v_add_f32_e32 v97, v97, v98
	v_add_f32_e32 v96, v96, v97
	v_mul_f32_e32 v97, v89, v89
	v_mul_f32_e32 v98, v91, v91
	v_fmac_f32_e32 v97, v88, v88
	v_fmac_f32_e32 v98, v90, v90
	v_add_f32_e32 v97, v97, v98
	v_add_f32_e32 v96, v97, v96
	v_mul_f32_e32 v97, v93, v93
	v_mul_f32_e32 v98, v95, v95
	v_fmac_f32_e32 v97, v92, v92
	v_fmac_f32_e32 v98, v94, v94
	v_add_f32_e32 v97, v97, v98
	v_add_f32_e32 v96, v97, v96
	ds_bpermute_b32 v97, v18, v96
	v_cvt_pk_bf16_f32 v80, v80, v81
	v_cvt_pk_bf16_f32 v81, v82, v83
	s_waitcnt lgkmcnt(0)
	v_add_f32_e32 v96, v96, v97
	ds_bpermute_b32 v97, v74, v96
	s_waitcnt lgkmcnt(0)
	v_add_f32_e32 v98, v96, v97
	ds_bpermute_b32 v99, v75, v98
	v_lshl_add_u64 v[96:97], v[42:43], 0, s[20:21]
	global_store_dwordx2 v[96:97], v[80:81], off sc1
	v_cvt_pk_bf16_f32 v80, v84, v85
	v_cvt_pk_bf16_f32 v81, v86, v87
	s_waitcnt lgkmcnt(0)
	v_add_f32_e32 v98, v98, v99
	ds_bpermute_b32 v99, v76, v98
	global_store_dwordx2 v[96:97], v[80:81], off offset:512 sc1
	v_cvt_pk_bf16_f32 v82, v88, v89
	v_cvt_pk_bf16_f32 v83, v90, v91
	global_store_dwordx2 v[96:97], v[82:83], off offset:1024 sc1
	s_waitcnt lgkmcnt(0)
	v_add_f32_e32 v84, v98, v99
	ds_bpermute_b32 v85, v77, v84
	v_cvt_pk_bf16_f32 v82, v92, v93
	v_cvt_pk_bf16_f32 v83, v94, v95
	global_store_dwordx2 v[96:97], v[82:83], off offset:1536 sc1
	s_waitcnt lgkmcnt(0)
	v_add_f32_e32 v80, v84, v85
	ds_bpermute_b32 v81, v78, v80
	s_and_saveexec_b64 s[20:21], s[4:5]
	s_cbranch_execnz .LBB0_710
	s_or_b64 exec, exec, s[20:21]
	s_waitcnt vmcnt(9)
	s_add_i32 s20, s24, s16
	s_cmpk_gt_i32 s20, 0x7fff
	s_cbranch_scc0 .LBB0_711

.LBB0_710:
	s_waitcnt lgkmcnt(0)
	v_add_f32_e32 v80, v80, v81
	v_fmamk_f32 v80, v80, 0x3a800000, v79
	v_rsq_f32_e32 v80, v80
	s_lshl_b64 s[28:29], s[6:7], 2
	s_add_u32 s28, s22, s28
	s_addc_u32 s29, s23, s29
	global_store_dword v19, v80, s[28:29] sc1
	s_waitcnt vmcnt(10)
	s_or_b64 exec, exec, s[20:21]
	s_add_i32 s20, s24, s16
	s_cmpk_gt_i32 s20, 0x7fff
	s_cbranch_scc1 .LBB0_709

.LBB0_712:
	v_and_b32_e32 v99, 0xffff0000, v17
	v_and_b32_e32 v98, 0xffff0000, v16
	v_lshlrev_b32_e32 v97, 16, v17
	v_lshlrev_b32_e32 v96, 16, v16
	v_pk_mul_f32 v[84:85], v[98:99], v[98:99]
	s_waitcnt lgkmcnt(0)
	v_pk_fma_f32 v[84:85], v[96:97], v[96:97], v[84:85]
	v_and_b32_e32 v105, 0xffff0000, v61
	v_and_b32_e32 v104, 0xffff0000, v60
	v_pk_add_f32 v[100:101], v[84:85], v[84:85] op_sel_hi:[0,1]
	v_lshlrev_b32_e32 v103, 16, v61
	v_lshlrev_b32_e32 v102, 16, v60
	v_pk_mul_f32 v[92:93], v[104:105], v[104:105]
	v_pk_fma_f32 v[92:93], v[102:103], v[102:103], v[92:93]
	v_lshlrev_b32_e32 v108, 16, v62
	v_pk_add_f32 v[106:107], v[92:93], v[92:93] op_sel_hi:[0,1]
	v_and_b32_e32 v109, 0xffff0000, v62
	v_lshlrev_b32_e32 v114, 16, v63
	v_lshlrev_b32_e32 v110, 16, v64
	v_mul_f32_e32 v111, v108, v108
	v_mul_f32_e32 v113, v109, v109
	v_and_b32_e32 v115, 0xffff0000, v63
	v_mul_f32_e32 v100, v114, v114
	v_mov_b32_e32 v112, v110
	v_pk_fma_f32 v[116:117], v[114:115], v[114:115], v[100:101] op_sel_hi:[1,1,0]
	v_and_b32_e32 v132, 0xffff0000, v64
	v_lshlrev_b32_e32 v118, 16, v65
	v_and_b32_e32 v119, 0xffff0000, v65
	v_pk_add_f32 v[112:113], v[110:111], v[112:113]
	v_mul_f32_e32 v116, v132, v132
	v_mul_f32_e32 v106, v118, v118
	v_mul_f32_e32 v100, v119, v119
	v_mul_f32_e32 v120, v110, v110
	v_mov_b32_e32 v121, v113
	v_pk_add_f32 v[112:113], v[120:121], v[116:117]
	v_pk_add_f32 v[100:101], v[106:107], v[100:101]
	v_mov_b32_e32 v128, v96
	v_pk_add_f32 v[100:101], v[112:113], v[100:101]
	v_mov_b32_e32 v129, v98
	v_add_f32_e32 v100, v100, v101
	ds_bpermute_b32 v101, v18, v100
	v_mov_b32_e32 v98, v97
	v_mov_b32_e32 v131, v104
	v_mov_b32_e32 v104, v103
	v_and_b32_e32 v117, 0xffff0000, v3
	s_waitcnt lgkmcnt(0)
	v_add_f32_e32 v106, v100, v101
	ds_bpermute_b32 v107, v74, v106
	v_lshlrev_b32_e32 v100, 16, v0
	v_and_b32_e32 v101, 0xffff0000, v0
	v_lshlrev_b32_e32 v120, 16, v4
	v_and_b32_e32 v121, 0xffff0000, v4
	s_waitcnt lgkmcnt(0)
	v_add_f32_e32 v111, v106, v107
	ds_bpermute_b32 v116, v75, v111
	v_lshlrev_b32_e32 v106, 16, v1
	v_and_b32_e32 v107, 0xffff0000, v1
	v_and_b32_e32 v127, 0xffff0000, v7
	v_lshlrev_b32_e32 v112, 16, v2
	s_waitcnt lgkmcnt(0)
	v_add_f32_e32 v111, v111, v116
	ds_bpermute_b32 v122, v76, v111
	v_lshlrev_b32_e32 v116, 16, v3
	v_and_b32_e32 v113, 0xffff0000, v2
	v_lshlrev_b32_e32 v124, 16, v6
	v_and_b32_e32 v125, 0xffff0000, v6
	s_waitcnt lgkmcnt(0)
	v_add_f32_e32 v111, v111, v122
	ds_bpermute_b32 v126, v77, v111
	v_lshlrev_b32_e32 v122, 16, v5
	v_and_b32_e32 v123, 0xffff0000, v5
	s_ashr_i32 s11, s10, 31
	s_lshl_b64 s[16:17], s[10:11], 11
	s_waitcnt lgkmcnt(0)
	v_add_f32_e32 v111, v111, v126
	ds_bpermute_b32 v130, v78, v111
	v_lshlrev_b32_e32 v126, 16, v7
	s_waitcnt lgkmcnt(0)
	v_add_f32_e32 v96, v111, v130
	v_fmamk_f32 v96, v96, 0x3a800000, v79
	v_rsq_f32_e32 v96, v96
	v_mov_b32_e32 v130, v102
	v_mov_b32_e32 v111, v132
	v_pk_mul_f32 v[98:99], v[96:97], v[98:99] op_sel_hi:[0,1]
	v_pk_fma_f32 v[82:83], v[202:203], v[98:99], v[106:107]
	v_pk_mul_f32 v[98:99], v[96:97], v[104:105] op_sel_hi:[0,1]
	v_pk_mul_f32 v[128:129], v[96:97], v[128:129] op_sel_hi:[0,1]
	v_pk_mul_f32 v[130:131], v[96:97], v[130:131] op_sel_hi:[0,1]
	v_pk_fma_f32 v[80:81], v[200:201], v[128:129], v[100:101]
	v_pk_mul_f32 v[100:101], v[114:115], v[96:97] op_sel_hi:[1,0]
	v_pk_fma_f32 v[86:87], v[206:207], v[98:99], v[116:117]
	v_pk_mul_f32 v[98:99], v[108:109], v[96:97] op_sel_hi:[1,0]
	v_pk_fma_f32 v[84:85], v[204:205], v[130:131], v[112:113]
	v_pk_fma_f32 v[88:89], v[208:209], v[98:99], v[120:121]
	v_pk_mul_f32 v[98:99], v[110:111], v[96:97] op_sel_hi:[1,0]
	v_pk_mul_f32 v[96:97], v[118:119], v[96:97] op_sel_hi:[1,0]
	v_pk_fma_f32 v[90:91], v[210:211], v[100:101], v[122:123]
	v_pk_fma_f32 v[94:95], v[214:215], v[96:97], v[126:127]
	v_mul_f32_e32 v96, v81, v81
	v_mul_f32_e32 v97, v83, v83
	v_fmac_f32_e32 v96, v80, v80
	v_fmac_f32_e32 v97, v82, v82
	v_pk_fma_f32 v[92:93], v[212:213], v[98:99], v[124:125]
	v_add_f32_e32 v96, v96, v97
	v_mul_f32_e32 v97, v85, v85
	v_mul_f32_e32 v98, v87, v87
	v_fmac_f32_e32 v97, v84, v84
	v_fmac_f32_e32 v98, v86, v86
	v_add_f32_e32 v97, v97, v98
	v_add_f32_e32 v96, v96, v97
	v_mul_f32_e32 v97, v89, v89
	v_mul_f32_e32 v98, v91, v91
	v_fmac_f32_e32 v97, v88, v88
	v_fmac_f32_e32 v98, v90, v90
	v_add_f32_e32 v97, v97, v98
	v_add_f32_e32 v96, v97, v96
	v_mul_f32_e32 v97, v93, v93
	v_mul_f32_e32 v98, v95, v95
	v_fmac_f32_e32 v97, v92, v92
	v_fmac_f32_e32 v98, v94, v94
	v_add_f32_e32 v97, v97, v98
	v_add_f32_e32 v96, v97, v96
	ds_bpermute_b32 v97, v18, v96
	v_cvt_pk_bf16_f32 v80, v80, v81
	v_cvt_pk_bf16_f32 v81, v82, v83
	s_waitcnt lgkmcnt(0)
	v_add_f32_e32 v96, v96, v97
	ds_bpermute_b32 v97, v74, v96
	s_waitcnt lgkmcnt(0)
	v_add_f32_e32 v98, v96, v97
	ds_bpermute_b32 v99, v75, v98
	v_lshl_add_u64 v[96:97], v[42:43], 0, s[16:17]
	global_store_dwordx2 v[96:97], v[80:81], off sc1
	v_cvt_pk_bf16_f32 v80, v84, v85
	v_cvt_pk_bf16_f32 v81, v86, v87
	s_waitcnt lgkmcnt(0)
	v_add_f32_e32 v98, v98, v99
	ds_bpermute_b32 v99, v76, v98
	global_store_dwordx2 v[96:97], v[80:81], off offset:512 sc1
	v_cvt_pk_bf16_f32 v82, v88, v89
	v_cvt_pk_bf16_f32 v83, v90, v91
	global_store_dwordx2 v[96:97], v[82:83], off offset:1024 sc1
	s_waitcnt lgkmcnt(0)
	v_add_f32_e32 v84, v98, v99
	ds_bpermute_b32 v85, v77, v84
	v_cvt_pk_bf16_f32 v82, v92, v93
	v_cvt_pk_bf16_f32 v83, v94, v95
	global_store_dwordx2 v[96:97], v[82:83], off offset:1536 sc1
	s_waitcnt lgkmcnt(0)
	v_add_f32_e32 v80, v84, v85
	ds_bpermute_b32 v81, v78, v80
	s_and_saveexec_b64 s[16:17], s[4:5]
	s_cbranch_execz .LBB0_714
	s_waitcnt lgkmcnt(0)
	v_add_f32_e32 v80, v80, v81
	v_fmamk_f32 v80, v80, 0x3a800000, v79
	v_rsq_f32_e32 v80, v80
	s_lshl_b64 s[18:19], s[10:11], 2
	s_add_u32 s18, s22, s18
	s_addc_u32 s19, s23, s19
	global_store_dword v19, v80, s[18:19] sc1
.LBB0_714:
	s_or_b64 exec, exec, s[16:17]
	v_and_b32_e32 v99, 0xffff0000, v67
	v_and_b32_e32 v98, 0xffff0000, v66
	v_lshlrev_b32_e32 v97, 16, v67
	v_lshlrev_b32_e32 v96, 16, v66
	v_pk_mul_f32 v[84:85], v[98:99], v[98:99]
	s_waitcnt lgkmcnt(0)
	v_pk_fma_f32 v[84:85], v[96:97], v[96:97], v[84:85]
	v_and_b32_e32 v105, 0xffff0000, v69
	v_and_b32_e32 v104, 0xffff0000, v68
	v_pk_add_f32 v[100:101], v[84:85], v[84:85] op_sel_hi:[0,1]
	v_lshlrev_b32_e32 v103, 16, v69
	v_lshlrev_b32_e32 v102, 16, v68
	v_pk_mul_f32 v[92:93], v[104:105], v[104:105]
	v_pk_fma_f32 v[92:93], v[102:103], v[102:103], v[92:93]
	v_lshlrev_b32_e32 v108, 16, v70
	v_pk_add_f32 v[106:107], v[92:93], v[92:93] op_sel_hi:[0,1]
	v_and_b32_e32 v109, 0xffff0000, v70
	v_lshlrev_b32_e32 v114, 16, v71
	v_lshlrev_b32_e32 v110, 16, v72
	v_mul_f32_e32 v111, v108, v108
	v_mul_f32_e32 v113, v109, v109
	v_and_b32_e32 v115, 0xffff0000, v71
	v_mul_f32_e32 v100, v114, v114
	v_mov_b32_e32 v112, v110
	v_pk_fma_f32 v[116:117], v[114:115], v[114:115], v[100:101] op_sel_hi:[1,1,0]
	v_and_b32_e32 v132, 0xffff0000, v72
	v_lshlrev_b32_e32 v118, 16, v73
	v_and_b32_e32 v119, 0xffff0000, v73
	v_pk_add_f32 v[112:113], v[110:111], v[112:113]
	v_mul_f32_e32 v116, v132, v132
	v_mul_f32_e32 v106, v118, v118
	v_mul_f32_e32 v100, v119, v119
	v_mul_f32_e32 v120, v110, v110
	v_mov_b32_e32 v121, v113
	v_pk_add_f32 v[112:113], v[120:121], v[116:117]
	v_pk_add_f32 v[100:101], v[106:107], v[100:101]
	v_mov_b32_e32 v128, v96
	v_pk_add_f32 v[100:101], v[112:113], v[100:101]
	v_mov_b32_e32 v129, v98
	v_add_f32_e32 v100, v100, v101
	ds_bpermute_b32 v101, v18, v100
	v_mov_b32_e32 v98, v97
	v_mov_b32_e32 v131, v104
	v_mov_b32_e32 v104, v103
	v_and_b32_e32 v117, 0xffff0000, v11
	s_waitcnt lgkmcnt(0)
	v_add_f32_e32 v106, v100, v101
	ds_bpermute_b32 v107, v74, v106
	v_lshlrev_b32_e32 v100, 16, v8
	v_and_b32_e32 v101, 0xffff0000, v8
	v_lshlrev_b32_e32 v120, 16, v12
	v_and_b32_e32 v121, 0xffff0000, v12
	s_waitcnt lgkmcnt(0)
	v_add_f32_e32 v111, v106, v107
	ds_bpermute_b32 v116, v75, v111
	v_lshlrev_b32_e32 v106, 16, v9
	v_and_b32_e32 v107, 0xffff0000, v9
	v_and_b32_e32 v127, 0xffff0000, v15
	v_lshlrev_b32_e32 v112, 16, v10
	s_waitcnt lgkmcnt(0)
	v_add_f32_e32 v111, v111, v116
	ds_bpermute_b32 v122, v76, v111
	v_lshlrev_b32_e32 v116, 16, v11
	v_and_b32_e32 v113, 0xffff0000, v10
	v_lshlrev_b32_e32 v124, 16, v14
	v_and_b32_e32 v125, 0xffff0000, v14
	s_waitcnt lgkmcnt(0)
	v_add_f32_e32 v111, v111, v122
	ds_bpermute_b32 v126, v77, v111
	v_lshlrev_b32_e32 v122, 16, v13
	v_and_b32_e32 v123, 0xffff0000, v13
	s_ashr_i32 s9, s8, 31
	s_lshl_b64 s[16:17], s[8:9], 11
	s_waitcnt lgkmcnt(0)
	v_add_f32_e32 v111, v111, v126
	ds_bpermute_b32 v130, v78, v111
	v_lshlrev_b32_e32 v126, 16, v15
	s_waitcnt lgkmcnt(0)
	v_add_f32_e32 v96, v111, v130
	v_fmamk_f32 v96, v96, 0x3a800000, v79
	v_rsq_f32_e32 v96, v96
	v_mov_b32_e32 v130, v102
	v_mov_b32_e32 v111, v132
	v_pk_mul_f32 v[98:99], v[96:97], v[98:99] op_sel_hi:[0,1]
	v_pk_fma_f32 v[82:83], v[202:203], v[98:99], v[106:107]
	v_pk_mul_f32 v[98:99], v[96:97], v[104:105] op_sel_hi:[0,1]
	v_pk_mul_f32 v[128:129], v[96:97], v[128:129] op_sel_hi:[0,1]
	v_pk_mul_f32 v[130:131], v[96:97], v[130:131] op_sel_hi:[0,1]
	v_pk_fma_f32 v[80:81], v[200:201], v[128:129], v[100:101]
	v_pk_mul_f32 v[100:101], v[114:115], v[96:97] op_sel_hi:[1,0]
	v_pk_fma_f32 v[86:87], v[206:207], v[98:99], v[116:117]
	v_pk_mul_f32 v[98:99], v[108:109], v[96:97] op_sel_hi:[1,0]
	v_pk_fma_f32 v[84:85], v[204:205], v[130:131], v[112:113]
	v_pk_fma_f32 v[88:89], v[208:209], v[98:99], v[120:121]
	v_pk_mul_f32 v[98:99], v[110:111], v[96:97] op_sel_hi:[1,0]
	v_pk_mul_f32 v[96:97], v[118:119], v[96:97] op_sel_hi:[1,0]
	v_pk_fma_f32 v[90:91], v[210:211], v[100:101], v[122:123]
	v_pk_fma_f32 v[94:95], v[214:215], v[96:97], v[126:127]
	v_mul_f32_e32 v96, v81, v81
	v_mul_f32_e32 v97, v83, v83
	v_fmac_f32_e32 v96, v80, v80
	v_fmac_f32_e32 v97, v82, v82
	v_pk_fma_f32 v[92:93], v[212:213], v[98:99], v[124:125]
	v_add_f32_e32 v96, v96, v97
	v_mul_f32_e32 v97, v85, v85
	v_mul_f32_e32 v98, v87, v87
	v_fmac_f32_e32 v97, v84, v84
	v_fmac_f32_e32 v98, v86, v86
	v_add_f32_e32 v97, v97, v98
	v_add_f32_e32 v96, v96, v97
	v_mul_f32_e32 v97, v89, v89
	v_mul_f32_e32 v98, v91, v91
	v_fmac_f32_e32 v97, v88, v88
	v_fmac_f32_e32 v98, v90, v90
	v_add_f32_e32 v97, v97, v98
	v_add_f32_e32 v96, v97, v96
	v_mul_f32_e32 v97, v93, v93
	v_mul_f32_e32 v98, v95, v95
	v_fmac_f32_e32 v97, v92, v92
	v_fmac_f32_e32 v98, v94, v94
	v_add_f32_e32 v97, v97, v98
	v_add_f32_e32 v96, v97, v96
	ds_bpermute_b32 v97, v18, v96
	v_cvt_pk_bf16_f32 v80, v80, v81
	v_cvt_pk_bf16_f32 v81, v82, v83
	s_waitcnt lgkmcnt(0)
	v_add_f32_e32 v96, v96, v97
	ds_bpermute_b32 v97, v74, v96
	s_waitcnt lgkmcnt(0)
	v_add_f32_e32 v98, v96, v97
	ds_bpermute_b32 v99, v75, v98
	v_lshl_add_u64 v[96:97], v[42:43], 0, s[16:17]
	global_store_dwordx2 v[96:97], v[80:81], off sc1
	v_cvt_pk_bf16_f32 v80, v84, v85
	v_cvt_pk_bf16_f32 v81, v86, v87
	s_waitcnt lgkmcnt(0)
	v_add_f32_e32 v98, v98, v99
	ds_bpermute_b32 v99, v76, v98
	global_store_dwordx2 v[96:97], v[80:81], off offset:512 sc1
	v_cvt_pk_bf16_f32 v82, v88, v89
	v_cvt_pk_bf16_f32 v83, v90, v91
	global_store_dwordx2 v[96:97], v[82:83], off offset:1024 sc1
	s_waitcnt lgkmcnt(0)
	v_add_f32_e32 v84, v98, v99
	ds_bpermute_b32 v85, v77, v84
	v_cvt_pk_bf16_f32 v82, v92, v93
	v_cvt_pk_bf16_f32 v83, v94, v95
	global_store_dwordx2 v[96:97], v[82:83], off offset:1536 sc1
	s_waitcnt lgkmcnt(0)
	v_add_f32_e32 v80, v84, v85
	ds_bpermute_b32 v81, v78, v80
	s_and_saveexec_b64 s[16:17], s[4:5]
	s_cbranch_execz .LBB0_701
	s_waitcnt lgkmcnt(0)
	v_add_f32_e32 v80, v80, v81
	v_fmamk_f32 v80, v80, 0x3a800000, v79
	v_rsq_f32_e32 v80, v80
	s_lshl_b64 s[18:19], s[8:9], 2
	s_add_u32 s18, s22, s18
	s_addc_u32 s19, s23, s19
	global_store_dword v19, v80, s[18:19] sc1
	s_branch .LBB0_701

.LBB0_920:
	s_and_b64 s[4:5], s[4:5], s[6:7]
	s_andn2_b64 vcc, exec, s[4:5]
	s_cbranch_vccnz .LBB0_938
	s_waitcnt vmcnt(0)
	v_mov_b32_e32 v1, s1
	v_mov_b32_e32 v0, v254
	v_mov_b32_e32 v4, s0
	v_mov_b32_e32 v5, s0
	v_readfirstlane_b32 s6, v4
	v_mov_b32_e32 v4, s1
	v_readfirstlane_b32 s4, v0
	v_readfirstlane_b32 s10, v5
	v_readfirstlane_b32 s11, v4
	v_mov_b32_e32 v4, s1
	v_mov_b32_e32 v5, s0
	s_lshl_b32 s3, s2, 3
	s_ashr_i32 s4, s4, 6
	v_mov_b32_e32 v2, s0
	s_add_i32 s16, s4, s3
	v_mov_b32_e32 v3, s0
	v_readfirstlane_b32 s7, v1
	v_mov_b32_e32 v1, s1
	v_readfirstlane_b32 s5, v4
	v_mov_b32_e32 v4, s1
	v_readfirstlane_b32 s4, v5
	s_cmpk_gt_i32 s16, 0x7fff
	v_readfirstlane_b32 s8, v3
	v_readfirstlane_b32 s9, v4
	v_readfirstlane_b32 s12, v2
	v_readfirstlane_b32 s13, v1
	s_cbranch_scc1 .LBB0_938
	s_load_dwordx2 s[12:13], s[12:13], 0xc0
	s_nop 0
	s_load_dwordx2 s[14:15], s[6:7], 0xc0
	s_load_dwordx2 s[18:19], s[10:11], 0xc0
	s_waitcnt lgkmcnt(0)
	s_lshl_b32 s17, s33, 3
	s_lshl_b32 s3, s33, 4
	v_and_b32_e32 v2, 63, v0
	s_add_u32 s22, s12, 0x3720c00
	s_addc_u32 s23, s13, 0
	s_add_i32 s6, s16, s17
	v_lshlrev_b32_e32 v18, 3, v2
	v_mov_b32_e32 v19, 0
	s_cmp_lt_i32 s6, 0x8000
	v_lshl_add_u64 v[0:1], s[14:15], 0, v[18:19]
	s_mov_b64 s[10:11], 0x4000000
	s_cselect_b32 s6, s6, s16
	v_lshl_add_u64 v[20:21], v[0:1], 0, s[10:11]
	v_lshl_add_u64 v[0:1], s[18:19], 0, v[18:19]
	s_mov_b64 s[12:13], 0x8000000
	s_ashr_i32 s17, s16, 31
	v_lshl_add_u64 v[22:23], v[0:1], 0, s[12:13]
	s_lshl_b64 s[12:13], s[16:17], 11
	v_lshl_add_u64 v[0:1], v[20:21], 0, s[12:13]
	s_ashr_i32 s7, s6, 31
	global_load_dwordx2 v[24:25], v[0:1], off
	global_load_dwordx2 v[26:27], v[0:1], off offset:512
	global_load_dwordx2 v[28:29], v[0:1], off offset:1024
	global_load_dwordx2 v[30:31], v[0:1], off offset:1536
	v_lshl_add_u64 v[0:1], v[22:23], 0, s[12:13]
	s_lshl_b64 s[12:13], s[6:7], 11
	global_load_dwordx2 v[32:33], v[0:1], off
	global_load_dwordx2 v[34:35], v[0:1], off offset:512
	global_load_dwordx2 v[36:37], v[0:1], off offset:1024
	global_load_dwordx2 v[38:39], v[0:1], off offset:1536
	v_lshl_add_u64 v[0:1], v[20:21], 0, s[12:13]
	global_load_dwordx2 v[44:45], v[0:1], off
	global_load_dwordx2 v[46:47], v[0:1], off offset:512
	global_load_dwordx2 v[48:49], v[0:1], off offset:1024
	global_load_dwordx2 v[50:51], v[0:1], off offset:1536
	v_lshl_add_u64 v[0:1], v[22:23], 0, s[12:13]
	global_load_dwordx2 v[52:53], v[0:1], off
	global_load_dwordx2 v[54:55], v[0:1], off offset:512
	global_load_dwordx2 v[56:57], v[0:1], off offset:1024
	global_load_dwordx2 v[58:59], v[0:1], off offset:1536
	s_load_dwordx2 s[12:13], s[4:5], 0x28
	s_load_dwordx2 s[14:15], s[8:9], 0xc0
	v_lshlrev_b32_e32 v0, 4, v2
	v_mov_b32_e32 v1, v19
	v_cmp_eq_u32_e64 s[4:5], 0, v2
	s_waitcnt lgkmcnt(0)
	v_lshl_add_u64 v[40:41], s[12:13], 0, v[0:1]
	v_lshl_add_u64 v[0:1], s[14:15], 0, v[18:19]
	v_lshl_add_u64 v[42:43], v[0:1], 0, s[10:11]
	v_mbcnt_lo_u32_b32 v0, -1, 0
	v_mbcnt_hi_u32_b32 v0, -1, v0
	v_and_b32_e32 v1, 64, v0
	v_add_u32_e32 v1, 64, v1
	v_xor_b32_e32 v2, 1, v0
	v_cmp_lt_i32_e32 vcc, v2, v1
	s_lshl_b32 s24, s33, 5
	s_mul_i32 s25, s33, 40
	v_cndmask_b32_e32 v2, v0, v2, vcc
	v_lshlrev_b32_e32 v18, 2, v2
	v_xor_b32_e32 v2, 2, v0
	v_cmp_lt_i32_e32 vcc, v2, v1
	s_mul_i32 s26, s33, 24
	v_mov_b32_e32 v79, 0x358637bd
	v_cndmask_b32_e32 v2, v0, v2, vcc
	v_lshlrev_b32_e32 v74, 2, v2
	v_xor_b32_e32 v2, 4, v0
	v_cmp_lt_i32_e32 vcc, v2, v1
	s_mov_b32 s12, s16
	s_nop 0
	v_cndmask_b32_e32 v2, v0, v2, vcc
	v_lshlrev_b32_e32 v75, 2, v2
	v_xor_b32_e32 v2, 8, v0
	v_cmp_lt_i32_e32 vcc, v2, v1
	s_nop 1
	v_cndmask_b32_e32 v2, v0, v2, vcc
	v_lshlrev_b32_e32 v76, 2, v2
	v_xor_b32_e32 v2, 16, v0
	v_cmp_lt_i32_e32 vcc, v2, v1
	s_nop 1
	v_cndmask_b32_e32 v2, v0, v2, vcc
	v_lshlrev_b32_e32 v77, 2, v2
	v_xor_b32_e32 v2, 32, v0
	v_cmp_lt_i32_e32 vcc, v2, v1
	s_nop 1
	v_cndmask_b32_e32 v0, v0, v2, vcc
	v_lshlrev_b32_e32 v78, 2, v0
	global_load_dwordx4 v[200:203], v[40:41], off
	global_load_dwordx4 v[204:207], v[40:41], off offset:1024
	global_load_dwordx4 v[208:211], v[40:41], off offset:2048
	global_load_dwordx4 v[212:215], v[40:41], off offset:3072
	s_waitcnt vmcnt(0)
	s_branch .LBB0_925

.LBB0_1227:
	s_and_b64 s[4:5], s[4:5], s[6:7]
	s_andn2_b64 vcc, exec, s[4:5]
	s_cbranch_vccnz .LBB0_1245
	s_waitcnt vmcnt(0)
	v_mov_b32_e32 v1, s1
	v_mov_b32_e32 v0, v254
	v_mov_b32_e32 v4, s0
	v_mov_b32_e32 v5, s1
	v_readfirstlane_b32 s6, v4
	v_mov_b32_e32 v4, s0
	v_readfirstlane_b32 s4, v0
	v_readfirstlane_b32 s10, v4
	v_readfirstlane_b32 s11, v5
	v_mov_b32_e32 v4, s0
	v_mov_b32_e32 v5, s1
	s_lshl_b32 s3, s2, 3
	s_ashr_i32 s4, s4, 6
	v_mov_b32_e32 v2, s0
	s_add_i32 s16, s4, s3
	v_mov_b32_e32 v3, s0
	v_readfirstlane_b32 s7, v1
	v_mov_b32_e32 v1, s1
	v_readfirstlane_b32 s4, v4
	v_mov_b32_e32 v4, s1
	v_readfirstlane_b32 s5, v5
	s_cmpk_gt_i32 s16, 0x7fff
	v_readfirstlane_b32 s8, v3
	v_readfirstlane_b32 s9, v4
	v_readfirstlane_b32 s12, v2
	v_readfirstlane_b32 s13, v1
	s_cbranch_scc1 .LBB0_1245
	s_load_dwordx2 s[12:13], s[12:13], 0xc0
	s_nop 0
	s_load_dwordx2 s[14:15], s[6:7], 0xc0
	s_load_dwordx2 s[18:19], s[10:11], 0xc0
	s_waitcnt lgkmcnt(0)
	s_lshl_b32 s17, s33, 3
	s_lshl_b32 s3, s33, 4
	v_and_b32_e32 v2, 63, v0
	s_add_u32 s22, s12, 0x3720c00
	s_addc_u32 s23, s13, 0
	s_add_i32 s6, s16, s17
	v_lshlrev_b32_e32 v18, 3, v2
	v_mov_b32_e32 v19, 0
	s_cmp_lt_i32 s6, 0x8000
	v_lshl_add_u64 v[0:1], s[14:15], 0, v[18:19]
	s_mov_b64 s[10:11], 0x4000000
	s_cselect_b32 s6, s6, s16
	v_lshl_add_u64 v[20:21], v[0:1], 0, s[10:11]
	v_lshl_add_u64 v[0:1], s[18:19], 0, v[18:19]
	s_mov_b64 s[12:13], 0x8000000
	s_ashr_i32 s17, s16, 31
	v_lshl_add_u64 v[22:23], v[0:1], 0, s[12:13]
	s_lshl_b64 s[12:13], s[16:17], 11
	v_lshl_add_u64 v[0:1], v[20:21], 0, s[12:13]
	s_ashr_i32 s7, s6, 31
	global_load_dwordx2 v[24:25], v[0:1], off
	global_load_dwordx2 v[26:27], v[0:1], off offset:512
	global_load_dwordx2 v[28:29], v[0:1], off offset:1024
	global_load_dwordx2 v[30:31], v[0:1], off offset:1536
	v_lshl_add_u64 v[0:1], v[22:23], 0, s[12:13]
	s_lshl_b64 s[12:13], s[6:7], 11
	global_load_dwordx2 v[32:33], v[0:1], off
	global_load_dwordx2 v[34:35], v[0:1], off offset:512
	global_load_dwordx2 v[36:37], v[0:1], off offset:1024
	global_load_dwordx2 v[38:39], v[0:1], off offset:1536
	v_lshl_add_u64 v[0:1], v[20:21], 0, s[12:13]
	global_load_dwordx2 v[44:45], v[0:1], off
	global_load_dwordx2 v[46:47], v[0:1], off offset:512
	global_load_dwordx2 v[48:49], v[0:1], off offset:1024
	global_load_dwordx2 v[50:51], v[0:1], off offset:1536
	v_lshl_add_u64 v[0:1], v[22:23], 0, s[12:13]
	global_load_dwordx2 v[52:53], v[0:1], off
	global_load_dwordx2 v[54:55], v[0:1], off offset:512
	global_load_dwordx2 v[56:57], v[0:1], off offset:1024
	global_load_dwordx2 v[58:59], v[0:1], off offset:1536
	s_load_dwordx2 s[12:13], s[4:5], 0x18
	s_load_dwordx2 s[14:15], s[8:9], 0xc0
	v_lshlrev_b32_e32 v0, 4, v2
	v_mov_b32_e32 v1, v19
	s_mov_b64 s[4:5], 0x1000
	s_waitcnt lgkmcnt(0)
	v_lshl_add_u64 v[0:1], s[12:13], 0, v[0:1]
	v_lshl_add_u64 v[40:41], v[0:1], 0, s[4:5]
	v_lshl_add_u64 v[0:1], s[14:15], 0, v[18:19]
	v_lshl_add_u64 v[42:43], v[0:1], 0, s[10:11]
	v_mbcnt_lo_u32_b32 v0, -1, 0
	v_mbcnt_hi_u32_b32 v0, -1, v0
	v_and_b32_e32 v1, 64, v0
	v_cmp_eq_u32_e64 s[4:5], 0, v2
	v_add_u32_e32 v1, 64, v1
	v_xor_b32_e32 v2, 1, v0
	v_cmp_lt_i32_e32 vcc, v2, v1
	s_lshl_b32 s24, s33, 5
	s_mul_i32 s25, s33, 40
	v_cndmask_b32_e32 v2, v0, v2, vcc
	v_lshlrev_b32_e32 v18, 2, v2
	v_xor_b32_e32 v2, 2, v0
	v_cmp_lt_i32_e32 vcc, v2, v1
	s_mul_i32 s26, s33, 24
	v_mov_b32_e32 v79, 0x358637bd
	v_cndmask_b32_e32 v2, v0, v2, vcc
	v_lshlrev_b32_e32 v74, 2, v2
	v_xor_b32_e32 v2, 4, v0
	v_cmp_lt_i32_e32 vcc, v2, v1
	s_mov_b32 s12, s16
	s_nop 0
	v_cndmask_b32_e32 v2, v0, v2, vcc
	v_lshlrev_b32_e32 v75, 2, v2
	v_xor_b32_e32 v2, 8, v0
	v_cmp_lt_i32_e32 vcc, v2, v1
	s_nop 1
	v_cndmask_b32_e32 v2, v0, v2, vcc
	v_lshlrev_b32_e32 v76, 2, v2
	v_xor_b32_e32 v2, 16, v0
	v_cmp_lt_i32_e32 vcc, v2, v1
	s_nop 1
	v_cndmask_b32_e32 v2, v0, v2, vcc
	v_lshlrev_b32_e32 v77, 2, v2
	v_xor_b32_e32 v2, 32, v0
	v_cmp_lt_i32_e32 vcc, v2, v1
	s_nop 1
	v_cndmask_b32_e32 v0, v0, v2, vcc
	v_lshlrev_b32_e32 v78, 2, v0
	global_load_dwordx4 v[200:203], v[40:41], off
	global_load_dwordx4 v[204:207], v[40:41], off offset:1024
	global_load_dwordx4 v[208:211], v[40:41], off offset:2048
	global_load_dwordx4 v[212:215], v[40:41], off offset:3072
	s_waitcnt vmcnt(0)
	s_branch .LBB0_1232
